# E12 + s_setprio 1/0 around the QK and PV MFMA clusters of both attention loops
# speedup vs baseline: 1.0020x; 1.0020x over previous
.LBB0_676:
	s_mov_b32 s6, 0xbfb8aa3b
	s_waitcnt lgkmcnt(4)
	v_pk_fma_f32 v[110:111], v[110:111], s[6:7], v[160:161] op_sel_hi:[1,0,0] neg_lo:[0,0,1] neg_hi:[0,0,1]
	v_pk_fma_f32 v[106:107], v[106:107], s[6:7], v[160:161] op_sel_hi:[1,0,0] neg_lo:[0,0,1] neg_hi:[0,0,1]
	v_pk_fma_f32 v[102:103], v[102:103], s[6:7], v[160:161] op_sel_hi:[1,0,0] neg_lo:[0,0,1] neg_hi:[0,0,1]
	v_pk_fma_f32 v[98:99], v[98:99], s[6:7], v[160:161] op_sel_hi:[1,0,0] neg_lo:[0,0,1] neg_hi:[0,0,1]
	v_pk_fma_f32 v[108:109], v[108:109], s[6:7], v[160:161] op_sel_hi:[1,0,0] neg_lo:[0,0,1] neg_hi:[0,0,1]
	v_pk_fma_f32 v[104:105], v[104:105], s[6:7], v[160:161] op_sel_hi:[1,0,0] neg_lo:[0,0,1] neg_hi:[0,0,1]
	v_pk_fma_f32 v[100:101], v[100:101], s[6:7], v[160:161] op_sel_hi:[1,0,0] neg_lo:[0,0,1] neg_hi:[0,0,1]
	v_pk_fma_f32 v[96:97], v[96:97], s[6:7], v[160:161] op_sel_hi:[1,0,0] neg_lo:[0,0,1] neg_hi:[0,0,1]
	s_waitcnt lgkmcnt(2)
	v_pk_fma_f32 v[126:127], v[122:123], s[6:7], v[160:161] op_sel_hi:[1,0,0] neg_lo:[0,0,1] neg_hi:[0,0,1]
	v_pk_fma_f32 v[122:123], v[118:119], s[6:7], v[160:161] op_sel_hi:[1,0,0] neg_lo:[0,0,1] neg_hi:[0,0,1]
	v_pk_fma_f32 v[118:119], v[114:115], s[6:7], v[160:161] op_sel_hi:[1,0,0] neg_lo:[0,0,1] neg_hi:[0,0,1]
	v_pk_fma_f32 v[114:115], v[12:13], s[6:7], v[160:161] op_sel_hi:[1,0,0] neg_lo:[0,0,1] neg_hi:[0,0,1]
	v_pk_fma_f32 v[124:125], v[120:121], s[6:7], v[160:161] op_sel_hi:[1,0,0] neg_lo:[0,0,1] neg_hi:[0,0,1]
	v_pk_fma_f32 v[120:121], v[116:117], s[6:7], v[160:161] op_sel_hi:[1,0,0] neg_lo:[0,0,1] neg_hi:[0,0,1]
	v_pk_fma_f32 v[116:117], v[112:113], s[6:7], v[160:161] op_sel_hi:[1,0,0] neg_lo:[0,0,1] neg_hi:[0,0,1]
	v_pk_fma_f32 v[112:113], v[10:11], s[6:7], v[160:161] op_sel_hi:[1,0,0] neg_lo:[0,0,1] neg_hi:[0,0,1]
	s_add_i32 s72, s95, s83
	s_setprio 1
	s_waitcnt lgkmcnt(1)
	v_mfma_f32_32x32x16_bf16 v[96:111], v[6:9], v[128:131], v[96:111]
	v_add_u32_e32 v0, s78, v170
	ds_read_b128 v[10:13], v0
	ds_read_b128 v[178:181], v0 offset:4096
	v_cvt_pk_bf16_f32 v148, v64, v65
	v_cvt_pk_bf16_f32 v149, v66, v67
	s_waitcnt lgkmcnt(2)
	v_mfma_f32_32x32x16_bf16 v[112:127], v[2:5], v[128:131], v[112:127]
	v_cvt_pk_bf16_f32 v150, v68, v69
	v_cvt_pk_bf16_f32 v151, v70, v71
	s_waitcnt lgkmcnt(1)
	v_mfma_f32_32x32x16_bf16 v[96:111], v[10:13], v[132:135], v[96:111]
	v_add_u32_e32 v0, s78, v171
	ds_read_b128 v[2:5], v0
	ds_read_b128 v[6:9], v0 offset:4096
	v_cvt_pk_bf16_f32 v152, v72, v73
	v_cvt_pk_bf16_f32 v153, v74, v75
	s_waitcnt lgkmcnt(2)
	v_mfma_f32_32x32x16_bf16 v[112:127], v[178:181], v[132:135], v[112:127]
	v_cvt_pk_bf16_f32 v154, v76, v77
	v_cvt_pk_bf16_f32 v155, v78, v79
	s_waitcnt lgkmcnt(1)
	v_mfma_f32_32x32x16_bf16 v[96:111], v[2:5], v[136:139], v[96:111]
	v_add_u32_e32 v0, s78, v172
	ds_read_b128 v[10:13], v0
	ds_read_b128 v[178:181], v0 offset:4096
	v_cvt_pk_bf16_f32 v156, v80, v81
	v_cvt_pk_bf16_f32 v157, v82, v83
	s_waitcnt lgkmcnt(2)
	v_mfma_f32_32x32x16_bf16 v[112:127], v[6:9], v[136:139], v[112:127]
	v_cvt_pk_bf16_f32 v158, v84, v85
	v_cvt_pk_bf16_f32 v159, v86, v87
	s_waitcnt lgkmcnt(1)
	v_mfma_f32_32x32x16_bf16 v[96:111], v[10:13], v[140:143], v[96:111]
	v_cvt_pk_bf16_f32 v144, v88, v89
	v_cvt_pk_bf16_f32 v145, v90, v91
	s_waitcnt lgkmcnt(0)
	v_mfma_f32_32x32x16_bf16 v[112:127], v[178:181], v[140:143], v[112:127]
	v_cvt_pk_bf16_f32 v146, v92, v93
	v_cvt_pk_bf16_f32 v147, v94, v95
	s_setprio 0
	s_cmp_lg_u32 s72, 0
	s_cbranch_scc1 .LBB0_678
	v_readlane_b32 s6, v226, 40
	v_readlane_b32 s7, v226, 41
	s_nop 5
	v_cndmask_b32_e64 v112, v112, v188, s[8:9]
	v_cndmask_b32_e64 v97, v97, v188, s[10:11]
	v_cndmask_b32_e64 v96, v96, v188, s[6:7]
	v_cndmask_b32_e64 v113, v113, v188, s[12:13]
	v_cndmask_b32_e64 v98, v98, v188, s[14:15]
	v_cndmask_b32_e64 v114, v114, v188, s[16:17]
	v_cndmask_b32_e64 v99, v99, v188, s[18:19]
	v_cndmask_b32_e64 v115, v115, v188, s[20:21]
	v_cndmask_b32_e64 v100, v100, v188, s[22:23]
	v_cndmask_b32_e64 v116, v116, v188, s[24:25]
	v_cndmask_b32_e64 v101, v101, v188, s[26:27]
	v_cndmask_b32_e64 v117, v117, v188, s[28:29]
	v_cndmask_b32_e64 v102, v102, v188, s[30:31]
	v_cndmask_b32_e64 v118, v118, v188, s[34:35]
	v_cndmask_b32_e64 v103, v103, v188, s[36:37]
	v_cndmask_b32_e64 v119, v119, v188, s[38:39]
	v_cndmask_b32_e64 v104, v104, v188, s[40:41]
	v_cndmask_b32_e64 v120, v120, v188, s[42:43]
	v_cndmask_b32_e64 v105, v105, v188, s[44:45]
	v_cndmask_b32_e64 v121, v121, v188, s[46:47]
	v_cndmask_b32_e64 v106, v106, v188, s[48:49]
	v_cndmask_b32_e64 v122, v122, v188, s[50:51]
	v_cndmask_b32_e64 v107, v107, v188, s[52:53]
	v_cndmask_b32_e64 v123, v123, v188, s[54:55]
	v_cndmask_b32_e64 v108, v108, v188, s[56:57]
	v_cndmask_b32_e64 v124, v124, v188, s[58:59]
	v_cndmask_b32_e64 v109, v109, v188, s[60:61]
	v_cndmask_b32_e64 v125, v125, v188, s[62:63]
	v_cndmask_b32_e64 v110, v110, v188, s[64:65]
	v_cndmask_b32_e64 v126, v126, v188, s[66:67]
	v_cndmask_b32_e64 v111, v111, v188, s[68:69]
	v_cndmask_b32_e64 v127, v127, v188, s[70:71]

; #define LAS __attribute__((address_space(3)))
; template <int TYPE> __device__ __forceinline__ void attn_unit(LAS unsigned char* lds, const AttnUnit& U) {
;     ...
;         if (resc) {
;             asm volatile("s_waitcnt lgkmcnt(0)" ::: "memory");
; #pragma unroll
;             for (int g = 0; g < 4; ++g) { const f32x4 al = *(const LAS f32x4*)(wsf + 8 * g + 4 * hi);
; #pragma unroll
;                 for (int i = 0; i < 4; ++i) { o0[4 * g + i] *= al[i]; o1[4 * g + i] *= al[i]; o2[4 * g + i] *= al[i]; } }
.LBB0_682:
	s_setprio 1
	v_exp_f32_e32 v64, v96
	v_exp_f32_e32 v65, v97
	v_exp_f32_e32 v80, v112
	v_mfma_f32_32x32x16_bf16 v[48:63], v[152:155], v[248:251], v[48:63]
	ds_read_b64_tr_b16 v[2:3], v0 offset:4096
	ds_read_b64_tr_b16 v[4:5], v0 offset:5120
	ds_read_b64_tr_b16 v[6:7], v14 offset:4096
	ds_read_b64_tr_b16 v[8:9], v14 offset:5120
	v_exp_f32_e32 v66, v98
	v_exp_f32_e32 v81, v113
	v_exp_f32_e32 v82, v114
	v_exp_f32_e32 v67, v99
	s_waitcnt lgkmcnt(6)
	v_mfma_f32_32x32x16_bf16 v[32:47], v[152:155], v[178:181], v[32:47]
	v_exp_f32_e32 v83, v115
	v_exp_f32_e32 v68, v100
	v_exp_f32_e32 v69, v101
	v_exp_f32_e32 v84, v116
	s_waitcnt lgkmcnt(4)
	v_mfma_f32_32x32x16_bf16 v[16:31], v[152:155], v[192:195], v[16:31]
	v_exp_f32_e32 v70, v102
	v_exp_f32_e32 v85, v117
	v_exp_f32_e32 v86, v118
	v_exp_f32_e32 v71, v103
	v_mfma_f32_32x32x16_bf16 v[48:63], v[156:159], v[248:251], v[48:63]
	ds_read_b64_tr_b16 v[228:229], v0 offset:6144
	ds_read_b64_tr_b16 v[230:231], v0 offset:7168
	ds_read_b64_tr_b16 v[232:233], v14 offset:6144
	ds_read_b64_tr_b16 v[234:235], v14 offset:7168
	v_exp_f32_e32 v87, v119
	v_exp_f32_e32 v72, v104
	v_exp_f32_e32 v73, v105
	s_waitcnt lgkmcnt(6)
	v_mfma_f32_32x32x16_bf16 v[32:47], v[156:159], v[2:5], v[32:47]
	v_exp_f32_e32 v88, v120
	v_exp_f32_e32 v74, v106
	v_exp_f32_e32 v89, v121
	s_waitcnt lgkmcnt(4)
	v_mfma_f32_32x32x16_bf16 v[16:31], v[156:159], v[6:9], v[16:31]
	v_exp_f32_e32 v90, v122
	v_exp_f32_e32 v75, v107
	v_exp_f32_e32 v91, v123
	v_mfma_f32_32x32x16_bf16 v[48:63], v[144:147], v[248:251], v[48:63]
	v_exp_f32_e32 v76, v108
	v_exp_f32_e32 v77, v109
	v_exp_f32_e32 v92, v124
	s_waitcnt lgkmcnt(2)
	v_mfma_f32_32x32x16_bf16 v[32:47], v[144:147], v[228:231], v[32:47]
	v_exp_f32_e32 v78, v110
	v_exp_f32_e32 v93, v125
	v_exp_f32_e32 v94, v126
	s_waitcnt lgkmcnt(0)
	v_mfma_f32_32x32x16_bf16 v[16:31], v[144:147], v[232:235], v[16:31]
	v_exp_f32_e32 v79, v111
	v_exp_f32_e32 v95, v127
	s_setprio 0
	s_andn2_b64 vcc, exec, s[72:73]
	s_cbranch_vccnz .LBB0_684
	s_waitcnt lgkmcnt(0)
	ds_read_b128 v[2:5], v177 offset:96
	ds_read_b128 v[6:9], v177 offset:64
	ds_read_b128 v[10:13], v177 offset:32
	ds_read_b128 v[96:99], v177
	s_waitcnt lgkmcnt(0)
	s_waitcnt lgkmcnt(3)
	v_pk_mul_f32 v[46:47], v[46:47], v[4:5]
	s_waitcnt lgkmcnt(2)
	v_pk_mul_f32 v[42:43], v[42:43], v[8:9]
	s_waitcnt lgkmcnt(1)
	v_pk_mul_f32 v[38:39], v[38:39], v[12:13]
	s_waitcnt lgkmcnt(0)
	v_pk_mul_f32 v[34:35], v[34:35], v[98:99]
	v_pk_mul_f32 v[44:45], v[44:45], v[2:3]
	v_pk_mul_f32 v[40:41], v[40:41], v[6:7]
	v_pk_mul_f32 v[36:37], v[36:37], v[10:11]
	v_pk_mul_f32 v[32:33], v[32:33], v[96:97]
	v_pk_mul_f32 v[30:31], v[30:31], v[4:5]
	v_pk_mul_f32 v[26:27], v[26:27], v[8:9]
	v_pk_mul_f32 v[22:23], v[22:23], v[12:13]
	v_pk_mul_f32 v[18:19], v[18:19], v[98:99]
	v_pk_mul_f32 v[28:29], v[28:29], v[2:3]
	v_pk_mul_f32 v[24:25], v[24:25], v[6:7]
	v_pk_mul_f32 v[20:21], v[20:21], v[10:11]
	v_pk_mul_f32 v[16:17], v[16:17], v[96:97]
	v_pk_mul_f32 v[62:63], v[62:63], v[4:5]
	v_pk_mul_f32 v[58:59], v[58:59], v[8:9]
	v_pk_mul_f32 v[54:55], v[54:55], v[12:13]
	v_pk_mul_f32 v[50:51], v[50:51], v[98:99]
	v_pk_mul_f32 v[60:61], v[60:61], v[2:3]
	v_pk_mul_f32 v[56:57], v[56:57], v[6:7]
	v_pk_mul_f32 v[52:53], v[52:53], v[10:11]
	v_pk_mul_f32 v[48:49], v[48:49], v[96:97]

.LBB0_748:
	s_add_i32 s72, s33, s93
	s_setprio 1
	s_waitcnt lgkmcnt(1)
	v_mfma_f32_32x32x16_bf16 v[128:143], v[6:9], v[144:147], v[96:111]
	v_add_u32_e32 v0, s78, v204
	ds_read_b128 v[10:13], v0
	ds_read_b128 v[212:215], v0 offset:4096
	v_cvt_pk_bf16_f32 v172, v80, v81
	v_cvt_pk_bf16_f32 v173, v82, v83
	v_cvt_pk_bf16_f32 v174, v84, v85
	v_cvt_pk_bf16_f32 v175, v86, v87
	s_waitcnt lgkmcnt(2)
	v_mfma_f32_32x32x16_bf16 v[112:127], v[2:5], v[144:147], v[96:111]
	s_waitcnt lgkmcnt(1)
	v_mfma_f32_32x32x16_bf16 v[128:143], v[10:13], v[148:151], v[128:143]
	v_add_u32_e32 v0, s78, v205
	ds_read_b128 v[2:5], v0
	ds_read_b128 v[6:9], v0 offset:4096
	v_cvt_pk_bf16_f32 v176, v88, v89
	v_cvt_pk_bf16_f32 v177, v90, v91
	s_waitcnt lgkmcnt(2)
	v_mfma_f32_32x32x16_bf16 v[112:127], v[212:215], v[148:151], v[112:127]
	v_cvt_pk_bf16_f32 v178, v92, v93
	v_cvt_pk_bf16_f32 v179, v94, v95
	s_waitcnt lgkmcnt(1)
	v_mfma_f32_32x32x16_bf16 v[128:143], v[2:5], v[152:155], v[128:143]
	v_add_u32_e32 v0, s78, v206
	ds_read_b128 v[10:13], v0
	ds_read_b128 v[212:215], v0 offset:4096
	v_cvt_pk_bf16_f32 v180, v64, v65
	v_cvt_pk_bf16_f32 v181, v66, v67
	s_waitcnt lgkmcnt(2)
	v_mfma_f32_32x32x16_bf16 v[112:127], v[6:9], v[152:155], v[112:127]
	v_cvt_pk_bf16_f32 v182, v68, v69
	v_cvt_pk_bf16_f32 v183, v70, v71
	s_waitcnt lgkmcnt(1)
	v_mfma_f32_32x32x16_bf16 v[128:143], v[10:13], v[156:159], v[128:143]
	v_add_u32_e32 v0, s78, v207
	ds_read_b128 v[2:5], v0
	ds_read_b128 v[6:9], v0 offset:2048
	v_cvt_pk_bf16_f32 v168, v72, v73
	v_cvt_pk_bf16_f32 v169, v74, v75
	s_waitcnt lgkmcnt(2)
	v_mfma_f32_32x32x16_bf16 v[112:127], v[212:215], v[156:159], v[112:127]
	v_cvt_pk_bf16_f32 v170, v76, v77
	v_cvt_pk_bf16_f32 v171, v78, v79
	s_waitcnt lgkmcnt(1)
	v_mfma_f32_32x32x16_bf16 v[128:143], v[2:5], v[160:163], v[128:143]
	v_add_u32_e32 v0, s78, v208
	ds_read_b128 v[10:13], v0
	ds_read_b128 v[212:215], v0 offset:2048
	s_waitcnt lgkmcnt(2)
	v_mfma_f32_32x32x16_bf16 v[112:127], v[6:9], v[160:163], v[112:127]
	s_waitcnt lgkmcnt(1)
	v_mfma_f32_32x32x16_bf16 v[128:143], v[10:13], v[164:167], v[128:143]
	s_waitcnt lgkmcnt(0)
	v_mfma_f32_32x32x16_bf16 v[112:127], v[212:215], v[164:167], v[112:127]
	s_setprio 0
	s_cmp_lg_u32 s72, 0
	s_cbranch_scc1 .LBB0_750
	v_readlane_b32 s40, v226, 40
	v_readlane_b32 s41, v226, 41
	s_nop 5
	v_cndmask_b32_e64 v143, v188, v143, s[6:7]
	v_cndmask_b32_e64 v142, v188, v142, s[10:11]
	v_cndmask_b32_e64 v141, v188, v141, s[12:13]
	v_cndmask_b32_e64 v140, v188, v140, s[14:15]
	v_cndmask_b32_e64 v139, v188, v139, s[16:17]
	v_cndmask_b32_e64 v138, v188, v138, s[18:19]
	v_cndmask_b32_e64 v137, v188, v137, s[20:21]
	v_cndmask_b32_e64 v136, v188, v136, s[22:23]
	v_cndmask_b32_e64 v135, v188, v135, s[24:25]
	v_cndmask_b32_e64 v134, v188, v134, s[26:27]
	v_cndmask_b32_e64 v133, v188, v133, s[28:29]
	v_cndmask_b32_e64 v132, v188, v132, s[30:31]
	v_cndmask_b32_e64 v131, v188, v131, s[34:35]
	v_cndmask_b32_e64 v130, v188, v130, s[36:37]
	v_cndmask_b32_e64 v129, v188, v129, s[38:39]
	v_cndmask_b32_e64 v128, v188, v128, s[40:41]
	v_cndmask_b32_e64 v127, v188, v127, s[8:9]
	v_cndmask_b32_e64 v126, v188, v126, s[42:43]
	v_cndmask_b32_e64 v125, v188, v125, s[44:45]
	v_cndmask_b32_e64 v124, v188, v124, s[46:47]
	v_cndmask_b32_e64 v123, v188, v123, s[48:49]
	v_cndmask_b32_e64 v122, v188, v122, s[50:51]
	v_cndmask_b32_e64 v121, v188, v121, s[52:53]
	v_cndmask_b32_e64 v120, v188, v120, s[54:55]
	v_cndmask_b32_e64 v119, v188, v119, s[56:57]
	v_cndmask_b32_e64 v118, v188, v118, s[58:59]
	v_cndmask_b32_e64 v117, v188, v117, s[60:61]
	v_cndmask_b32_e64 v116, v188, v116, s[62:63]
	v_cndmask_b32_e64 v115, v188, v115, s[64:65]
	v_cndmask_b32_e64 v114, v188, v114, s[66:67]
	v_cndmask_b32_e64 v113, v188, v113, s[68:69]
	v_cndmask_b32_e64 v112, v188, v112, s[70:71]

; #define LAS __attribute__((address_space(3)))
; template <int TYPE> __device__ __forceinline__ void attn_unit(LAS unsigned char* lds, const AttnUnit& U) {
;     ...
;         if (resc) {
;             asm volatile("s_waitcnt lgkmcnt(0)" ::: "memory");
; #pragma unroll
;             for (int g = 0; g < 4; ++g) { const f32x4 al = *(const LAS f32x4*)(wsf + 8 * g + 4 * hi);
; #pragma unroll
;                 for (int i = 0; i < 4; ++i) { o0[4 * g + i] *= al[i]; o1[4 * g + i] *= al[i]; o2[4 * g + i] *= al[i]; } }
.LBB0_754:
	s_setprio 1
	v_exp_f32_e32 v80, v128
	v_exp_f32_e32 v81, v129
	v_exp_f32_e32 v64, v112
	v_mfma_f32_32x32x16_bf16 v[48:63], v[176:179], v[248:251], v[48:63]
	ds_read_b64_tr_b16 v[2:3], v0 offset:4096
	ds_read_b64_tr_b16 v[4:5], v0 offset:5120
	ds_read_b64_tr_b16 v[6:7], v14 offset:4096
	ds_read_b64_tr_b16 v[8:9], v14 offset:5120
	v_exp_f32_e32 v82, v130
	v_exp_f32_e32 v65, v113
	v_exp_f32_e32 v66, v114
	v_exp_f32_e32 v83, v131
	s_waitcnt lgkmcnt(6)
	v_mfma_f32_32x32x16_bf16 v[32:47], v[176:179], v[212:215], v[32:47]
	v_exp_f32_e32 v67, v115
	v_exp_f32_e32 v84, v132
	v_exp_f32_e32 v85, v133
	v_exp_f32_e32 v68, v116
	s_waitcnt lgkmcnt(4)
	v_mfma_f32_32x32x16_bf16 v[16:31], v[176:179], v[216:219], v[16:31]
	v_exp_f32_e32 v86, v134
	v_exp_f32_e32 v69, v117
	v_exp_f32_e32 v70, v118
	v_exp_f32_e32 v87, v135
	v_mfma_f32_32x32x16_bf16 v[48:63], v[180:183], v[248:251], v[48:63]
	ds_read_b64_tr_b16 v[228:229], v0 offset:6144
	ds_read_b64_tr_b16 v[230:231], v0 offset:7168
	ds_read_b64_tr_b16 v[232:233], v14 offset:6144
	ds_read_b64_tr_b16 v[234:235], v14 offset:7168
	v_exp_f32_e32 v71, v119
	v_exp_f32_e32 v88, v136
	v_exp_f32_e32 v89, v137
	s_waitcnt lgkmcnt(6)
	v_mfma_f32_32x32x16_bf16 v[32:47], v[180:183], v[2:5], v[32:47]
	v_exp_f32_e32 v72, v120
	v_exp_f32_e32 v90, v138
	v_exp_f32_e32 v73, v121
	s_waitcnt lgkmcnt(4)
	v_mfma_f32_32x32x16_bf16 v[16:31], v[180:183], v[6:9], v[16:31]
	v_exp_f32_e32 v74, v122
	v_exp_f32_e32 v91, v139
	v_exp_f32_e32 v75, v123
	v_mfma_f32_32x32x16_bf16 v[48:63], v[168:171], v[248:251], v[48:63]
	v_exp_f32_e32 v92, v140
	v_exp_f32_e32 v93, v141
	v_exp_f32_e32 v76, v124
	s_waitcnt lgkmcnt(2)
	v_mfma_f32_32x32x16_bf16 v[32:47], v[168:171], v[228:231], v[32:47]
	v_exp_f32_e32 v94, v142
	v_exp_f32_e32 v77, v125
	v_exp_f32_e32 v78, v126
	s_waitcnt lgkmcnt(0)
	v_mfma_f32_32x32x16_bf16 v[16:31], v[168:171], v[232:235], v[16:31]
	v_exp_f32_e32 v95, v143
	v_exp_f32_e32 v79, v127
	s_setprio 0
	s_andn2_b64 vcc, exec, s[72:73]
	s_cbranch_vccnz .LBB0_756
	s_waitcnt lgkmcnt(0)
	ds_read_b128 v[2:5], v210 offset:96
	ds_read_b128 v[6:9], v210 offset:64
	ds_read_b128 v[10:13], v210 offset:32
	ds_read_b128 v[112:115], v210
	s_waitcnt lgkmcnt(0)
	s_waitcnt lgkmcnt(3)
	v_pk_mul_f32 v[46:47], v[46:47], v[4:5]
	s_waitcnt lgkmcnt(2)
	v_pk_mul_f32 v[42:43], v[42:43], v[8:9]
	s_waitcnt lgkmcnt(1)
	v_pk_mul_f32 v[38:39], v[38:39], v[12:13]
	s_waitcnt lgkmcnt(0)
	v_pk_mul_f32 v[34:35], v[34:35], v[114:115]
	v_pk_mul_f32 v[44:45], v[44:45], v[2:3]
	v_pk_mul_f32 v[40:41], v[40:41], v[6:7]
	v_pk_mul_f32 v[36:37], v[36:37], v[10:11]
	v_pk_mul_f32 v[32:33], v[32:33], v[112:113]
	v_pk_mul_f32 v[30:31], v[30:31], v[4:5]
	v_pk_mul_f32 v[26:27], v[26:27], v[8:9]
	v_pk_mul_f32 v[22:23], v[22:23], v[12:13]
	v_pk_mul_f32 v[18:19], v[18:19], v[114:115]
	v_pk_mul_f32 v[28:29], v[28:29], v[2:3]
	v_pk_mul_f32 v[24:25], v[24:25], v[6:7]
	v_pk_mul_f32 v[20:21], v[20:21], v[10:11]
	v_pk_mul_f32 v[16:17], v[16:17], v[112:113]
	v_pk_mul_f32 v[62:63], v[62:63], v[4:5]
	v_pk_mul_f32 v[58:59], v[58:59], v[8:9]
	v_pk_mul_f32 v[54:55], v[54:55], v[12:13]
	v_pk_mul_f32 v[50:51], v[50:51], v[114:115]
	v_pk_mul_f32 v[60:61], v[60:61], v[2:3]
	v_pk_mul_f32 v[56:57], v[56:57], v[6:7]
	v_pk_mul_f32 v[52:53], v[52:53], v[10:11]
	v_pk_mul_f32 v[48:49], v[48:49], v[112:113]
